# shadow5 + rdhoist on top of shadow3: P1 LDS/DMA address + m0 set-up rotated across the K-loop back-edge into P8 MFMA gaps; S5 FULL chunk output step issues all 8 LDS fragment reads up front
# speedup vs baseline: 1.0087x; 1.0012x over previous
.LBB0_125:
	v_add_u32_e32 v178, s42, v164
	v_ashrrev_i32_e32 v179, 31, v178
	v_lshlrev_b64 v[178:179], 12, v[178:179]
	v_lshl_add_u64 v[180:181], v[146:147], 0, v[178:179]
	global_load_dwordx2 v[174:175], v[180:181], off
	v_add3_u32 v178, v164, s42, 16
	v_ashrrev_i32_e32 v179, 31, v178
	v_lshlrev_b64 v[178:179], 12, v[178:179]
	v_lshl_add_u64 v[180:181], v[146:147], 0, v[178:179]
	global_load_dwordx2 v[176:177], v[180:181], off
	s_min_u32 s44, s42, 0x7f0
	s_add_i32 s44, s44, s43
	s_waitcnt lgkmcnt(0)
	v_pk_mul_f32 v[6:7], v[6:7], v[8:9] op_sel_hi:[1,0]
	v_pk_mul_f32 v[4:5], v[4:5], v[8:9] op_sel_hi:[1,0]
	v_pk_mul_f32 v[2:3], v[2:3], v[8:9] op_sel_hi:[1,0]
	v_pk_mul_f32 v[0:1], v[0:1], v[8:9] op_sel_hi:[1,0]
	v_pk_mul_f32 v[6:7], v[86:87], v[6:7]
	v_pk_mul_f32 v[4:5], v[84:85], v[4:5]
	v_pk_mul_f32 v[2:3], v[82:83], v[2:3]
	v_pk_mul_f32 v[0:1], v[80:81], v[0:1]
	v_cmp_gt_i32_e32 vcc, s44, v123
	s_nop 1
	v_cndmask_b32_e32 v3, 0, v3, vcc
	v_cndmask_b32_e32 v2, 0, v2, vcc
	v_cndmask_b32_e32 v1, 0, v1, vcc
	v_cndmask_b32_e32 v0, 0, v0, vcc
	v_cndmask_b32_e32 v7, 0, v7, vcc
	v_cndmask_b32_e32 v6, 0, v6, vcc
	v_cndmask_b32_e32 v5, 0, v5, vcc
	v_cndmask_b32_e32 v4, 0, v4, vcc
	v_cvt_pk_bf16_f32 v32, v4, v5
	v_cvt_pk_bf16_f32 v33, v6, v7
	v_cvt_pk_bf16_f32 v34, v0, v1
	v_cvt_pk_bf16_f32 v35, v2, v3
	v_cmp_gt_i32_e32 vcc, s44, v155
	s_nop 0
	v_mfma_f32_32x32x16_bf16 v[16:31], v[32:35], v[92:95], 0
	s_nop 0
	v_mfma_f32_32x32x16_bf16 v[0:15], v[32:35], v[96:99], 0
	s_nop 0
	v_mfma_f32_32x32x16_bf16 v[48:63], v[32:35], v[100:103], 0
	s_nop 9
	v_permlane32_swap_b32_e32 v16, v0
	v_mov_b32_e32 v169, v16
	v_permlane32_swap_b32_e32 v17, v1
	v_permlane32_swap_b32_e32 v18, v2
	s_nop 0
	v_mfma_f32_32x32x16_bf16 v[32:47], v[32:35], v[104:107], 0
	v_permlane32_swap_b32_e32 v19, v3
	v_permlane32_swap_b32_e32 v20, v4
	v_permlane32_swap_b32_e32 v21, v5
	v_permlane32_swap_b32_e32 v22, v6
	s_nop 7
	v_permlane32_swap_b32_e32 v48, v32
	v_mov_b32_e32 v168, v48
	v_pk_fma_f32 v[168:169], v[150:151], v[140:141], v[168:169] op_sel:[0,1,0] op_sel_hi:[1,0,1]
	v_permlane32_swap_b32_e32 v49, v33
	v_pk_fma_f32 v[140:141], v[152:153], v[140:141], v[168:169]
	v_mov_b32_e32 v48, v17
	v_pk_fma_f32 v[16:17], v[138:139], v[140:141], v[48:49]
	v_pk_mov_b32 v[168:169], v[140:141], v[140:141] op_sel:[1,0]
	v_pk_fma_f32 v[16:17], v[152:153], v[140:141], v[16:17] op_sel:[0,1,0] op_sel_hi:[1,0,1]
	v_cvt_pk_bf16_f32 v167, v168, v169
	v_mov_b32_e32 v168, v0
	v_mov_b32_e32 v169, v32
	v_cvt_pk_bf16_f32 v0, v16, v17
	v_add_u32_e32 v32, 0x2000, v156
	v_permlane32_swap_b32_e32 v50, v34
	ds_write2_b32 v32, v167, v0 offset0:64 offset1:132
	v_mov_b32_e32 v32, v1
	v_mov_b32_e32 v0, v18
	v_mov_b32_e32 v1, v50
	v_pk_fma_f32 v[0:1], v[138:139], v[16:17], v[0:1] op_sel:[0,1,0] op_sel_hi:[1,0,1]
	v_permlane32_swap_b32_e32 v51, v35
	v_pk_fma_f32 v[0:1], v[152:153], v[16:17], v[0:1]
	v_mov_b32_e32 v50, v19
	v_pk_fma_f32 v[18:19], v[138:139], v[0:1], v[50:51] op_sel:[0,1,0] op_sel_hi:[1,0,1]
	v_cvt_pk_bf16_f32 v48, v0, v1
	v_pk_fma_f32 v[0:1], v[152:153], v[0:1], v[18:19]
	v_mov_b32_e32 v16, v2
	v_cvt_pk_bf16_f32 v2, v0, v1
	v_add_u32_e32 v18, 0x2200, v156
	ds_write2_b32 v18, v48, v2 offset0:72 offset1:140
	v_pk_fma_f32 v[18:19], v[138:139], v[0:1], v[168:169] op_sel:[0,1,0] op_sel_hi:[1,0,1]
	v_mov_b32_e32 v17, v34
	v_pk_fma_f32 v[0:1], v[152:153], v[0:1], v[18:19]
	v_mov_b32_e32 v34, v3
	v_pk_fma_f32 v[18:19], v[138:139], v[0:1], v[32:33] op_sel:[0,1,0] op_sel_hi:[1,0,1]
	v_cvt_pk_bf16_f32 v2, v0, v1
	v_pk_fma_f32 v[0:1], v[152:153], v[0:1], v[18:19]
	v_add_u32_e32 v19, 0x2400, v156
	v_pk_fma_f32 v[16:17], v[138:139], v[0:1], v[16:17] op_sel:[0,1,0] op_sel_hi:[1,0,1]
	v_cvt_pk_bf16_f32 v18, v0, v1
	v_pk_fma_f32 v[0:1], v[152:153], v[0:1], v[16:17]
	ds_write2_b32 v19, v2, v18 offset0:80 offset1:148
	v_pk_fma_f32 v[2:3], v[138:139], v[0:1], v[34:35] op_sel:[0,1,0] op_sel_hi:[1,0,1]
	v_cvt_pk_bf16_f32 v16, v0, v1
	v_pk_fma_f32 v[0:1], v[152:153], v[0:1], v[2:3]
	v_permlane32_swap_b32_e32 v52, v36
	v_cvt_pk_bf16_f32 v2, v0, v1
	v_add_u32_e32 v3, 0x2600, v156
	ds_write2_b32 v3, v16, v2 offset0:88 offset1:156
	v_mov_b32_e32 v2, v20
	v_mov_b32_e32 v3, v52
	v_pk_fma_f32 v[2:3], v[138:139], v[0:1], v[2:3] op_sel:[0,1,0] op_sel_hi:[1,0,1]
	v_permlane32_swap_b32_e32 v53, v37
	v_pk_fma_f32 v[0:1], v[152:153], v[0:1], v[2:3]
	v_mov_b32_e32 v52, v21
	v_pk_fma_f32 v[16:17], v[138:139], v[0:1], v[52:53] op_sel:[0,1,0] op_sel_hi:[1,0,1]
	v_cvt_pk_bf16_f32 v18, v0, v1
	v_pk_fma_f32 v[0:1], v[152:153], v[0:1], v[16:17]
	v_mov_b32_e32 v2, v4
	v_cvt_pk_bf16_f32 v4, v0, v1
	v_add_u32_e32 v16, 0x2800, v156
	v_permlane32_swap_b32_e32 v54, v38
	v_mov_b32_e32 v3, v36
	ds_write2_b32 v16, v18, v4 offset0:96 offset1:164
	v_mov_b32_e32 v36, v5
	v_mov_b32_e32 v4, v22
	v_mov_b32_e32 v5, v54
	v_pk_fma_f32 v[4:5], v[138:139], v[0:1], v[4:5] op_sel:[0,1,0] op_sel_hi:[1,0,1]
	v_permlane32_swap_b32_e32 v23, v7
	v_pk_fma_f32 v[0:1], v[152:153], v[0:1], v[4:5]
	v_permlane32_swap_b32_e32 v55, v39
	v_mov_b32_e32 v54, v23
	v_pk_fma_f32 v[16:17], v[138:139], v[0:1], v[54:55] op_sel:[0,1,0] op_sel_hi:[1,0,1]
	v_cvt_pk_bf16_f32 v18, v0, v1
	v_pk_fma_f32 v[0:1], v[152:153], v[0:1], v[16:17]
	v_mov_b32_e32 v4, v6
	v_pk_fma_f32 v[2:3], v[138:139], v[0:1], v[2:3] op_sel:[0,1,0] op_sel_hi:[1,0,1]
	v_cvt_pk_bf16_f32 v6, v0, v1
	v_pk_fma_f32 v[0:1], v[152:153], v[0:1], v[2:3]
	v_add_u32_e32 v16, 0x2a00, v156
	v_pk_fma_f32 v[2:3], v[138:139], v[0:1], v[36:37] op_sel:[0,1,0] op_sel_hi:[1,0,1]
	ds_write2_b32 v16, v18, v6 offset0:104 offset1:172
	v_cvt_pk_bf16_f32 v6, v0, v1
	v_pk_fma_f32 v[0:1], v[152:153], v[0:1], v[2:3]
	v_mov_b32_e32 v5, v38
	v_cvt_pk_bf16_f32 v2, v0, v1
	v_add_u32_e32 v3, 0x2c00, v156
	ds_write2_b32 v3, v6, v2 offset0:112 offset1:180
	v_pk_fma_f32 v[2:3], v[138:139], v[0:1], v[4:5] op_sel:[0,1,0] op_sel_hi:[1,0,1]
	v_mov_b32_e32 v38, v7
	v_pk_fma_f32 v[0:1], v[152:153], v[0:1], v[2:3]
	v_permlane32_swap_b32_e32 v24, v8
	v_pk_fma_f32 v[2:3], v[138:139], v[0:1], v[38:39] op_sel:[0,1,0] op_sel_hi:[1,0,1]
	v_cvt_pk_bf16_f32 v4, v0, v1
	v_pk_fma_f32 v[16:17], v[152:153], v[0:1], v[2:3]
	v_permlane32_swap_b32_e32 v56, v40
	v_cvt_pk_bf16_f32 v0, v16, v17
	v_add_u32_e32 v1, 0x2e00, v156
	ds_write2_b32 v1, v4, v0 offset0:120 offset1:188
	v_mov_b32_e32 v0, v24
	v_mov_b32_e32 v1, v56
	v_pk_fma_f32 v[0:1], v[138:139], v[16:17], v[0:1] op_sel:[0,1,0] op_sel_hi:[1,0,1]
	v_permlane32_swap_b32_e32 v25, v9
	v_pk_fma_f32 v[0:1], v[152:153], v[16:17], v[0:1]
	v_permlane32_swap_b32_e32 v57, v41
	v_mov_b32_e32 v56, v25
	v_pk_fma_f32 v[4:5], v[138:139], v[0:1], v[56:57] op_sel:[0,1,0] op_sel_hi:[1,0,1]
	v_permlane32_swap_b32_e32 v26, v10
	v_permlane32_swap_b32_e32 v58, v42
	v_cvt_pk_bf16_f32 v6, v0, v1
	v_pk_fma_f32 v[0:1], v[152:153], v[0:1], v[4:5]
	v_mov_b32_e32 v20, v26
	v_mov_b32_e32 v21, v58
	v_permlane32_swap_b32_e32 v27, v11
	v_pk_fma_f32 v[20:21], v[138:139], v[0:1], v[20:21] op_sel:[0,1,0] op_sel_hi:[1,0,1]
	v_cvt_pk_bf16_f32 v4, v0, v1
	v_permlane32_swap_b32_e32 v59, v43
	v_pk_fma_f32 v[0:1], v[152:153], v[0:1], v[20:21]
	v_mov_b32_e32 v58, v27
	v_pk_fma_f32 v[20:21], v[138:139], v[0:1], v[58:59] op_sel:[0,1,0] op_sel_hi:[1,0,1]
	v_mov_b32_e32 v2, v8
	v_mov_b32_e32 v3, v40
	v_cvt_pk_bf16_f32 v22, v0, v1
	v_pk_fma_f32 v[0:1], v[152:153], v[0:1], v[20:21]
	v_mov_b32_e32 v40, v9
	v_pk_fma_f32 v[2:3], v[138:139], v[0:1], v[2:3] op_sel:[0,1,0] op_sel_hi:[1,0,1]
	v_cvt_pk_bf16_f32 v20, v0, v1
	v_pk_fma_f32 v[0:1], v[152:153], v[0:1], v[2:3]
	v_add_u32_e32 v21, 0x3400, v156
	v_pk_fma_f32 v[2:3], v[138:139], v[0:1], v[40:41] op_sel:[0,1,0] op_sel_hi:[1,0,1]
	ds_write2_b32 v21, v22, v20 offset0:8 offset1:76
	v_cvt_pk_bf16_f32 v20, v0, v1
	v_pk_fma_f32 v[0:1], v[152:153], v[0:1], v[2:3]
	v_mov_b32_e32 v3, v42
	v_cvt_pk_bf16_f32 v2, v0, v1
	ds_write2_b32 v21, v20, v2 offset0:144 offset1:212
	v_mov_b32_e32 v2, v10
	v_pk_fma_f32 v[2:3], v[138:139], v[0:1], v[2:3] op_sel:[0,1,0] op_sel_hi:[1,0,1]
	v_mov_b32_e32 v10, v43
	v_pk_fma_f32 v[0:1], v[152:153], v[0:1], v[2:3]
	v_add_u32_e32 v5, 0x3000, v156
	v_pk_fma_f32 v[2:3], v[150:151], v[0:1], v[10:11]
	v_cvt_pk_bf16_f32 v20, v0, v1
	v_pk_fma_f32 v[0:1], v[152:153], v[0:1], v[2:3] op_sel:[0,1,0] op_sel_hi:[1,0,1]
	v_permlane32_swap_b32_e32 v28, v12
	v_permlane32_swap_b32_e32 v60, v44
	v_pk_mov_b32 v[2:3], v[0:1], v[0:1] op_sel:[1,0]
	ds_write2_b32 v5, v6, v4 offset0:128 offset1:196
	v_mov_b32_e32 v4, v60
	v_mov_b32_e32 v5, v28
	v_cvt_pk_bf16_f32 v2, v2, v3
	v_add_u32_e32 v10, 0x3800, v156
	ds_write2_b32 v10, v20, v2 offset0:24 offset1:92
	v_pk_fma_f32 v[2:3], v[150:151], v[0:1], v[4:5] op_sel:[0,1,0] op_sel_hi:[1,0,1]
	v_permlane32_swap_b32_e32 v61, v45
	v_pk_fma_f32 v[0:1], v[152:153], v[0:1], v[2:3]
	v_permlane32_swap_b32_e32 v29, v13
	v_mov_b32_e32 v28, v61
	v_pk_mov_b32 v[2:3], v[0:1], v[0:1] op_sel:[1,0]
	v_permlane32_swap_b32_e32 v30, v14
	v_cvt_pk_bf16_f32 v4, v2, v3
	v_pk_fma_f32 v[2:3], v[150:151], v[0:1], v[28:29] op_sel:[0,1,0] op_sel_hi:[1,0,1]
	v_permlane32_swap_b32_e32 v62, v46
	v_pk_fma_f32 v[0:1], v[152:153], v[0:1], v[2:3]
	v_mov_b32_e32 v8, v62
	v_pk_mov_b32 v[2:3], v[0:1], v[0:1] op_sel:[1,0]
	v_mov_b32_e32 v9, v30
	v_cvt_pk_bf16_f32 v2, v2, v3
	ds_write2_b32 v10, v4, v2 offset0:160 offset1:228
	v_pk_fma_f32 v[2:3], v[150:151], v[0:1], v[8:9] op_sel:[0,1,0] op_sel_hi:[1,0,1]
	v_permlane32_swap_b32_e32 v63, v47
	v_pk_fma_f32 v[0:1], v[152:153], v[0:1], v[2:3]
	v_permlane32_swap_b32_e32 v31, v15
	v_mov_b32_e32 v30, v63
	v_pk_mov_b32 v[2:3], v[0:1], v[0:1] op_sel:[1,0]
	v_mov_b32_e32 v6, v44
	v_cvt_pk_bf16_f32 v4, v2, v3
	v_pk_fma_f32 v[2:3], v[150:151], v[0:1], v[30:31] op_sel:[0,1,0] op_sel_hi:[1,0,1]
	v_mov_b32_e32 v7, v12
	v_pk_fma_f32 v[0:1], v[152:153], v[0:1], v[2:3]
	v_add_u32_e32 v5, 0x3c00, v156
	v_pk_mov_b32 v[2:3], v[0:1], v[0:1] op_sel:[1,0]
	v_mov_b32_e32 v12, v45
	v_cvt_pk_bf16_f32 v2, v2, v3
	ds_write2_b32 v5, v4, v2 offset0:40 offset1:108
	v_pk_fma_f32 v[2:3], v[150:151], v[0:1], v[6:7] op_sel:[0,1,0] op_sel_hi:[1,0,1]
	v_mov_b32_e32 v18, v46
	v_pk_fma_f32 v[0:1], v[152:153], v[0:1], v[2:3]
	v_mov_b32_e32 v19, v14
	v_pk_mov_b32 v[2:3], v[0:1], v[0:1] op_sel:[1,0]
	v_mov_b32_e32 v14, v47
	v_cvt_pk_bf16_f32 v4, v2, v3
	v_pk_fma_f32 v[2:3], v[150:151], v[0:1], v[12:13] op_sel:[0,1,0] op_sel_hi:[1,0,1]
	v_add_u32_e32 v6, v157, v158
	v_pk_fma_f32 v[0:1], v[152:153], v[0:1], v[2:3]
	s_nop 0
	v_pk_mov_b32 v[2:3], v[0:1], v[0:1] op_sel:[1,0]
	s_nop 0
	v_cvt_pk_bf16_f32 v2, v2, v3
	ds_write2_b32 v5, v4, v2 offset0:176 offset1:244
	v_pk_fma_f32 v[2:3], v[150:151], v[0:1], v[18:19] op_sel:[0,1,0] op_sel_hi:[1,0,1]
	s_nop 0
	v_pk_fma_f32 v[0:1], v[152:153], v[0:1], v[2:3]
	s_nop 0
	v_pk_mov_b32 v[2:3], v[0:1], v[0:1] op_sel:[1,0]
	s_nop 0
	v_cvt_pk_bf16_f32 v4, v2, v3
	v_pk_fma_f32 v[2:3], v[150:151], v[0:1], v[14:15] op_sel:[0,1,0] op_sel_hi:[1,0,1]
	s_nop 0
	v_pk_fma_f32 v[140:141], v[152:153], v[0:1], v[2:3]
	s_nop 0
	v_pk_mov_b32 v[0:1], v[140:141], v[140:141] op_sel:[1,0]
	s_nop 0
	v_cvt_pk_bf16_f32 v0, v0, v1
	v_add_u32_e32 v1, 0x4000, v156
	ds_write2_b32 v1, v4, v0 offset0:56 offset1:124
	s_waitcnt lgkmcnt(0)
	ds_read_b128 v[0:3], v6 offset:8448
	ds_read_b128 v[8:11], v6 offset:8512
	ds_read_b128 v[200:203], v6 offset:8576
	ds_read_b128 v[12:15], v6 offset:8640
	ds_read_b128 v[204:207], v6 offset:12800
	ds_read_b128 v[208:211], v6 offset:12864
	ds_read_b128 v[212:215], v6 offset:12928
	ds_read_b128 v[216:219], v6 offset:12992
	s_waitcnt lgkmcnt(7)
	v_mfma_f32_16x16x32_bf16 v[0:3], v[64:67], v[0:3], 0
	s_waitcnt lgkmcnt(6)
	v_mfma_f32_16x16x32_bf16 v[0:3], v[68:71], v[8:11], v[0:3]
	s_waitcnt lgkmcnt(5)
	v_mfma_f32_16x16x32_bf16 v[0:3], v[72:75], v[200:203], v[0:3]
	s_waitcnt lgkmcnt(4)
	v_mfma_f32_16x16x32_bf16 v[0:3], v[76:79], v[12:15], v[0:3]
	s_and_saveexec_b64 s[78:79], vcc
	s_cbranch_execz .LBB0_127
	v_add_u32_e32 v4, s42, v164
	v_ashrrev_i32_e32 v5, 31, v4
	v_lshlrev_b64 v[4:5], 12, v[4:5]
	ds_read_b32 v8, v165
	s_waitcnt vmcnt(1)
	v_lshlrev_b32_e32 v12, 16, v174
	v_and_b32_e32 v13, 0xffff0000, v174
	v_lshlrev_b32_e32 v10, 16, v175
	v_and_b32_e32 v11, 0xffff0000, v175
	s_waitcnt lgkmcnt(0)
	v_pk_mul_f32 v[14:15], v[8:9], v[10:11] op_sel_hi:[0,1]
	v_pk_mul_f32 v[12:13], v[8:9], v[12:13] op_sel_hi:[0,1]
	s_nop 0
	v_pk_mul_f32 v[8:9], v[182:183], v[12:13]
	s_nop 0
	v_pk_fma_f32 v[0:1], v[88:89], v[8:9], v[0:1]
	v_pk_mul_f32 v[10:11], v[184:185], v[14:15]
	v_mul_f32_e32 v7, 0x3d372713, v0
	v_mul_f32_e32 v7, v0, v7
	v_fma_f32 v7, v0, v7, v0
	v_mul_f32_e32 v7, 0xbfcc422a, v7
	v_mul_f32_e32 v7, 0x3fb8aa3b, v7
	v_exp_f32_e32 v7, v7
	v_pk_fma_f32 v[2:3], v[90:91], v[10:11], v[2:3]
	v_add_f32_e32 v7, 1.0, v7
	v_rcp_f32_e32 v8, v7
	v_mul_f32_e32 v7, 0x3d372713, v1
	v_mul_f32_e32 v7, v1, v7
	v_fma_f32 v7, v1, v7, v1
	v_mul_f32_e32 v7, 0xbfcc422a, v7
	v_mul_f32_e32 v7, 0x3fb8aa3b, v7
	v_exp_f32_e32 v7, v7
	s_nop 0
	v_add_f32_e32 v7, 1.0, v7
	v_rcp_f32_e32 v9, v7
	v_mul_f32_e32 v7, 0x3d372713, v2
	v_mul_f32_e32 v7, v2, v7
	v_fma_f32 v7, v2, v7, v2
	v_mul_f32_e32 v7, 0xbfcc422a, v7
	v_mul_f32_e32 v7, 0x3fb8aa3b, v7
	v_exp_f32_e32 v7, v7
	v_pk_mul_f32 v[0:1], v[0:1], v[8:9]
	v_add_f32_e32 v7, 1.0, v7
	v_rcp_f32_e32 v8, v7
	v_mul_f32_e32 v7, 0x3d372713, v3
	v_mul_f32_e32 v7, v3, v7
	v_fma_f32 v7, v3, v7, v3
	v_mul_f32_e32 v7, 0xbfcc422a, v7
	v_mul_f32_e32 v7, 0x3fb8aa3b, v7
	v_exp_f32_e32 v7, v7
	v_cvt_pk_bf16_f32 v0, v0, v1
	v_add_f32_e32 v7, 1.0, v7
	v_rcp_f32_e32 v9, v7
	s_nop 0
	v_pk_mul_f32 v[2:3], v[2:3], v[8:9]
	s_nop 0
	v_cvt_pk_bf16_f32 v1, v2, v3
	v_lshl_add_u64 v[2:3], v[142:143], 0, v[4:5]
	global_store_dwordx2 v[2:3], v[0:1], off
.LBB0_127:
	s_or_b64 exec, exec, s[78:79]
	s_nop 4
	v_cmp_gt_i32_e32 vcc, s44, v159
	s_waitcnt lgkmcnt(0)
	v_mfma_f32_16x16x32_bf16 v[0:3], v[64:67], v[204:207], 0
	v_mfma_f32_16x16x32_bf16 v[0:3], v[68:71], v[208:211], v[0:3]
	v_mfma_f32_16x16x32_bf16 v[0:3], v[72:75], v[212:215], v[0:3]
	v_mfma_f32_16x16x32_bf16 v[0:3], v[76:79], v[216:219], v[0:3]
	s_and_saveexec_b64 s[78:79], vcc
	s_cbranch_execz .LBB0_122
	v_add3_u32 v4, v164, s42, 16
	v_ashrrev_i32_e32 v5, 31, v4
	v_lshlrev_b64 v[4:5], 12, v[4:5]
	ds_read_b32 v6, v165 offset:64
	s_waitcnt vmcnt(1)
	v_lshlrev_b32_e32 v10, 16, v176
	v_and_b32_e32 v11, 0xffff0000, v176
	v_lshlrev_b32_e32 v8, 16, v177
	v_and_b32_e32 v9, 0xffff0000, v177
	s_waitcnt lgkmcnt(0)
	v_pk_mul_f32 v[12:13], v[6:7], v[8:9] op_sel_hi:[0,1]
	v_pk_mul_f32 v[10:11], v[6:7], v[10:11] op_sel_hi:[0,1]
	s_nop 0
	v_pk_mul_f32 v[6:7], v[182:183], v[10:11]
	s_nop 0
	v_pk_fma_f32 v[0:1], v[88:89], v[6:7], v[0:1]
	v_pk_mul_f32 v[8:9], v[184:185], v[12:13]
	v_mul_f32_e32 v6, 0x3d372713, v0
	v_mul_f32_e32 v7, 0x3d372713, v1
	v_mul_f32_e32 v6, v0, v6
	v_mul_f32_e32 v7, v1, v7
	v_fma_f32 v6, v0, v6, v0
	v_fma_f32 v7, v1, v7, v1
	v_mul_f32_e32 v6, 0xbfcc422a, v6
	v_mul_f32_e32 v7, 0xbfcc422a, v7
	v_mul_f32_e32 v6, 0x3fb8aa3b, v6
	v_mul_f32_e32 v7, 0x3fb8aa3b, v7
	v_exp_f32_e32 v6, v6
	v_exp_f32_e32 v7, v7
	v_pk_fma_f32 v[2:3], v[90:91], v[8:9], v[2:3]
	v_add_f32_e32 v6, 1.0, v6
	v_add_f32_e32 v7, 1.0, v7
	v_rcp_f32_e32 v6, v6
	v_rcp_f32_e32 v7, v7
	s_nop 0
	v_pk_mul_f32 v[0:1], v[0:1], v[6:7]
	v_mul_f32_e32 v6, 0x3d372713, v2
	v_mul_f32_e32 v7, 0x3d372713, v3
	v_mul_f32_e32 v6, v2, v6
	v_mul_f32_e32 v7, v3, v7
	v_fma_f32 v6, v2, v6, v2
	v_fma_f32 v7, v3, v7, v3
	v_mul_f32_e32 v6, 0xbfcc422a, v6
	v_mul_f32_e32 v7, 0xbfcc422a, v7
	v_mul_f32_e32 v6, 0x3fb8aa3b, v6
	v_mul_f32_e32 v7, 0x3fb8aa3b, v7
	v_exp_f32_e32 v6, v6
	v_exp_f32_e32 v7, v7
	v_cvt_pk_bf16_f32 v0, v0, v1
	v_add_f32_e32 v6, 1.0, v6
	v_add_f32_e32 v7, 1.0, v7
	v_rcp_f32_e32 v6, v6
	v_rcp_f32_e32 v7, v7
	s_nop 0
	v_pk_mul_f32 v[2:3], v[2:3], v[6:7]
	s_nop 0
	v_cvt_pk_bf16_f32 v1, v2, v3
	v_lshl_add_u64 v[2:3], v[142:143], 0, v[4:5]
	global_store_dwordx2 v[2:3], v[0:1], off
	s_branch .LBB0_122

.LBB0_521:
	s_add_i32 s50, s30, -2
	s_add_u32 s72, s72, 0x80
	s_addc_u32 s73, s73, 0
	s_add_u32 s78, s74, 0x100
	v_mov_b32_e32 v0, 0
	s_addc_u32 s79, s75, 0
	s_mov_b32 s74, 0
	v_mov_b32_e32 v1, v0
	v_mov_b64_e32 v[2:3], v[0:1]
	v_mov_b64_e32 v[4:5], v[0:1]
	v_mov_b64_e32 v[6:7], v[0:1]
	v_mov_b64_e32 v[8:9], v[0:1]
	v_mov_b64_e32 v[10:11], v[0:1]
	v_mov_b64_e32 v[12:13], v[0:1]
	v_mov_b64_e32 v[14:15], v[0:1]
	v_mov_b64_e32 v[16:17], v[0:1]
	v_mov_b64_e32 v[18:19], v[0:1]
	v_mov_b64_e32 v[20:21], v[0:1]
	v_mov_b64_e32 v[22:23], v[0:1]
	v_mov_b64_e32 v[24:25], v[0:1]
	v_mov_b64_e32 v[26:27], v[0:1]
	v_mov_b64_e32 v[28:29], v[0:1]
	v_mov_b64_e32 v[30:31], v[0:1]
	v_mov_b64_e32 v[32:33], v[0:1]
	v_mov_b64_e32 v[34:35], v[0:1]
	v_mov_b64_e32 v[36:37], v[0:1]
	v_mov_b64_e32 v[38:39], v[0:1]
	v_mov_b64_e32 v[40:41], v[0:1]
	v_mov_b64_e32 v[42:43], v[0:1]
	v_mov_b64_e32 v[44:45], v[0:1]
	v_mov_b64_e32 v[46:47], v[0:1]
	v_mov_b64_e32 v[48:49], v[0:1]
	v_mov_b64_e32 v[50:51], v[0:1]
	v_mov_b64_e32 v[52:53], v[0:1]
	v_mov_b64_e32 v[54:55], v[0:1]
	v_mov_b64_e32 v[56:57], v[0:1]
	v_mov_b64_e32 v[58:59], v[0:1]
	v_mov_b64_e32 v[60:61], v[0:1]
	v_mov_b64_e32 v[62:63], v[0:1]
	v_mov_b64_e32 v[64:65], v[0:1]
	v_mov_b64_e32 v[66:67], v[0:1]
	v_mov_b64_e32 v[68:69], v[0:1]
	v_mov_b64_e32 v[70:71], v[0:1]
	v_mov_b64_e32 v[72:73], v[0:1]
	v_mov_b64_e32 v[74:75], v[0:1]
	v_mov_b64_e32 v[76:77], v[0:1]
	v_mov_b64_e32 v[78:79], v[0:1]
	v_mov_b64_e32 v[80:81], v[0:1]
	v_mov_b64_e32 v[82:83], v[0:1]
	v_mov_b64_e32 v[84:85], v[0:1]
	v_mov_b64_e32 v[86:87], v[0:1]
	v_mov_b64_e32 v[88:89], v[0:1]
	v_mov_b64_e32 v[90:91], v[0:1]
	v_mov_b64_e32 v[92:93], v[0:1]
	v_mov_b64_e32 v[94:95], v[0:1]
	v_mov_b64_e32 v[96:97], v[0:1]
	v_mov_b64_e32 v[98:99], v[0:1]
	v_mov_b64_e32 v[100:101], v[0:1]
	v_mov_b64_e32 v[102:103], v[0:1]
	v_mov_b64_e32 v[104:105], v[0:1]
	v_mov_b64_e32 v[106:107], v[0:1]
	v_mov_b64_e32 v[108:109], v[0:1]
	v_mov_b64_e32 v[110:111], v[0:1]
	v_mov_b64_e32 v[112:113], v[0:1]
	v_mov_b64_e32 v[114:115], v[0:1]
	v_mov_b64_e32 v[116:117], v[0:1]
	v_mov_b64_e32 v[118:119], v[0:1]
	v_mov_b64_e32 v[120:121], v[0:1]
	v_mov_b64_e32 v[122:123], v[0:1]
	v_mov_b64_e32 v[124:125], v[0:1]
	v_mov_b64_e32 v[126:127], v[0:1]
	s_add_i32 vcc_hi, 0, 0x10000
	v_add_u32_e32 v140, vcc_hi, v237
	v_lshl_add_u64 v[176:177], s[72:73], 0, v[206:207]
	v_lshl_add_u64 v[178:179], s[72:73], 0, v[208:209]
	s_add_i32 m0, s93, 0xc000
.LBB0_522:
	s_waitcnt lgkmcnt(0)
	ds_read_b128 v[128:131], v140
	ds_read_b128 v[132:135], v140 offset:1024
	ds_read_b128 v[136:139], v140 offset:2048
	ds_read_b128 v[140:143], v140 offset:3072
	ds_read_b128 v[144:147], v240
	ds_read_b128 v[148:151], v240 offset:1024
	ds_read_b128 v[152:155], v240 offset:2048
	ds_read_b128 v[156:159], v240 offset:3072
	ds_read_b128 v[160:163], v240 offset:4096
	ds_read_b128 v[164:167], v240 offset:5120
	ds_read_b128 v[168:171], v240 offset:6144
	ds_read_b128 v[172:175], v240 offset:7168
	global_load_lds_dwordx4 v[176:177], off
	s_add_i32 m0, s93, 0xe000
	s_nop 0
	global_load_lds_dwordx4 v[178:179], off
	s_waitcnt lgkmcnt(8)
	s_barrier
	s_waitcnt lgkmcnt(0)
	v_mfma_f32_16x16x32_bf16 v[124:127], v[128:131], v[144:147], v[124:127]
	s_add_i32 vcc_lo, s74, 2
	v_mfma_f32_16x16x32_bf16 v[120:123], v[136:139], v[144:147], v[120:123]
	s_add_u32 s76, s72, 0x80
	v_mfma_f32_16x16x32_bf16 v[116:119], v[128:131], v[152:155], v[116:119]
	s_addc_u32 s75, s73, 0
	v_mfma_f32_16x16x32_bf16 v[112:115], v[136:139], v[152:155], v[112:115]
	s_cmp_eq_u32 s50, s74
	v_mfma_f32_16x16x32_bf16 v[100:103], v[128:131], v[160:163], v[100:103]
	s_cselect_b32 s74, s68, s76
	v_mfma_f32_16x16x32_bf16 v[96:99], v[136:139], v[160:163], v[96:99]
	s_cselect_b32 s75, s69, s75
	v_mfma_f32_16x16x32_bf16 v[84:87], v[128:131], v[168:171], v[84:87]
	s_cselect_b32 s77, s71, s79
	v_mfma_f32_16x16x32_bf16 v[80:83], v[136:139], v[168:171], v[80:83]
	s_cselect_b32 s76, s70, s78
	v_mfma_f32_16x16x32_bf16 v[124:127], v[132:135], v[148:151], v[124:127]
	s_add_i32 s31, 0, 0x14000
	v_mfma_f32_16x16x32_bf16 v[120:123], v[140:143], v[148:151], v[120:123]
	s_add_i32 vcc_hi, vcc_hi, s87
	v_mfma_f32_16x16x32_bf16 v[116:119], v[132:135], v[156:159], v[116:119]
	v_add_u32_e32 v188, s31, v237
	v_mfma_f32_16x16x32_bf16 v[112:115], v[140:143], v[156:159], v[112:115]
	v_lshl_add_u64 v[210:211], s[76:77], 0, v[196:197]
	v_mfma_f32_16x16x32_bf16 v[100:103], v[132:135], v[164:167], v[100:103]
	s_mov_b32 m0, vcc_hi
	v_mfma_f32_16x16x32_bf16 v[96:99], v[140:143], v[164:167], v[96:99]
	v_mfma_f32_16x16x32_bf16 v[84:87], v[132:135], v[172:175], v[84:87]
	v_mfma_f32_16x16x32_bf16 v[80:83], v[140:143], v[172:175], v[80:83]
	s_barrier
	ds_read_b128 v[176:179], v188
	ds_read_b128 v[180:183], v188 offset:1024
	ds_read_b128 v[184:187], v188 offset:2048
	ds_read_b128 v[188:191], v188 offset:3072
	global_load_lds_dwordx4 v[210:211], off
	v_lshl_add_u64 v[212:213], s[76:77], 0, v[200:201]
	s_add_i32 m0, vcc_hi, 0x2000
	s_nop 0
	global_load_lds_dwordx4 v[212:213], off
	s_barrier
	s_waitcnt lgkmcnt(0)
	v_mfma_f32_16x16x32_bf16 v[108:111], v[176:179], v[144:147], v[108:111]
	v_mfma_f32_16x16x32_bf16 v[104:107], v[184:187], v[144:147], v[104:107]
	v_mfma_f32_16x16x32_bf16 v[92:95], v[176:179], v[152:155], v[92:95]
	v_mfma_f32_16x16x32_bf16 v[88:91], v[184:187], v[152:155], v[88:91]
	v_mfma_f32_16x16x32_bf16 v[76:79], v[176:179], v[160:163], v[76:79]
	v_mfma_f32_16x16x32_bf16 v[72:75], v[184:187], v[160:163], v[72:75]
	v_mfma_f32_16x16x32_bf16 v[68:71], v[176:179], v[168:171], v[68:71]
	v_mfma_f32_16x16x32_bf16 v[64:67], v[184:187], v[168:171], v[64:67]
	v_mfma_f32_16x16x32_bf16 v[108:111], v[180:183], v[148:151], v[108:111]
	s_mov_b32 m0, s93
	v_mfma_f32_16x16x32_bf16 v[104:107], v[188:191], v[148:151], v[104:107]
	v_lshl_add_u64 v[214:215], s[74:75], 0, v[194:195]
	v_mfma_f32_16x16x32_bf16 v[92:95], v[180:183], v[156:159], v[92:95]
	v_mfma_f32_16x16x32_bf16 v[88:91], v[188:191], v[156:159], v[88:91]
	v_mfma_f32_16x16x32_bf16 v[76:79], v[180:183], v[164:167], v[76:79]
	v_mfma_f32_16x16x32_bf16 v[72:75], v[188:191], v[164:167], v[72:75]
	v_mfma_f32_16x16x32_bf16 v[68:71], v[180:183], v[172:175], v[68:71]
	v_mfma_f32_16x16x32_bf16 v[64:67], v[188:191], v[172:175], v[64:67]
	s_barrier
	ds_read_b128 v[144:147], v240 offset:16384
	ds_read_b128 v[148:151], v240 offset:17408
	ds_read_b128 v[152:155], v240 offset:18432
	ds_read_b128 v[156:159], v240 offset:19456
	ds_read_b128 v[160:163], v240 offset:20480
	ds_read_b128 v[164:167], v240 offset:21504
	ds_read_b128 v[168:171], v240 offset:22528
	ds_read_b128 v[172:175], v240 offset:23552
	global_load_lds_dwordx4 v[214:215], off
	v_lshl_add_u64 v[216:217], s[74:75], 0, v[198:199]
	s_mov_b32 m0, s54
	s_nop 0
	global_load_lds_dwordx4 v[216:217], off
	s_barrier
	s_waitcnt lgkmcnt(0)
	v_mfma_f32_16x16x32_bf16 v[60:63], v[128:131], v[144:147], v[60:63]
	v_mfma_f32_16x16x32_bf16 v[56:59], v[136:139], v[144:147], v[56:59]
	v_mfma_f32_16x16x32_bf16 v[52:55], v[128:131], v[152:155], v[52:55]
	v_mfma_f32_16x16x32_bf16 v[48:51], v[136:139], v[152:155], v[48:51]
	v_mfma_f32_16x16x32_bf16 v[36:39], v[128:131], v[160:163], v[36:39]
	v_mfma_f32_16x16x32_bf16 v[32:35], v[136:139], v[160:163], v[32:35]
	v_mfma_f32_16x16x32_bf16 v[20:23], v[128:131], v[168:171], v[20:23]
	v_mfma_f32_16x16x32_bf16 v[16:19], v[136:139], v[168:171], v[16:19]
	v_mfma_f32_16x16x32_bf16 v[60:63], v[132:135], v[148:151], v[60:63]
	s_add_u32 s76, s76, s20
	v_mfma_f32_16x16x32_bf16 v[56:59], v[140:143], v[148:151], v[56:59]
	s_addc_u32 s77, s77, 0
	v_mfma_f32_16x16x32_bf16 v[52:55], v[132:135], v[156:159], v[52:55]
	s_add_i32 s31, s31, s87
	v_mfma_f32_16x16x32_bf16 v[48:51], v[140:143], v[156:159], v[48:51]
	v_lshl_add_u64 v[218:219], s[76:77], 0, v[196:197]
	v_mfma_f32_16x16x32_bf16 v[36:39], v[132:135], v[164:167], v[36:39]
	s_mov_b32 m0, s31
	v_mfma_f32_16x16x32_bf16 v[32:35], v[140:143], v[164:167], v[32:35]
	v_lshl_add_u64 v[220:221], s[76:77], 0, v[200:201]
	v_mfma_f32_16x16x32_bf16 v[20:23], v[132:135], v[172:175], v[20:23]
	v_mfma_f32_16x16x32_bf16 v[16:19], v[140:143], v[172:175], v[16:19]
	s_barrier
	global_load_lds_dwordx4 v[218:219], off
	s_add_i32 m0, s31, 0x2000
	s_nop 0
	global_load_lds_dwordx4 v[220:221], off
	s_waitcnt vmcnt(6)
	s_barrier
	v_mfma_f32_16x16x32_bf16 v[44:47], v[176:179], v[144:147], v[44:47]
	v_mfma_f32_16x16x32_bf16 v[40:43], v[184:187], v[144:147], v[40:43]
	v_mfma_f32_16x16x32_bf16 v[28:31], v[176:179], v[152:155], v[28:31]
	v_mfma_f32_16x16x32_bf16 v[24:27], v[184:187], v[152:155], v[24:27]
	v_mfma_f32_16x16x32_bf16 v[12:15], v[176:179], v[160:163], v[12:15]
	v_mfma_f32_16x16x32_bf16 v[8:11], v[184:187], v[160:163], v[8:11]
	v_mfma_f32_16x16x32_bf16 v[4:7], v[176:179], v[168:171], v[4:7]
	v_mfma_f32_16x16x32_bf16 v[0:3], v[184:187], v[168:171], v[0:3]
	v_mfma_f32_16x16x32_bf16 v[44:47], v[180:183], v[148:151], v[44:47]
	s_add_i32 s31, 0, 0x18000
	v_mfma_f32_16x16x32_bf16 v[40:43], v[188:191], v[148:151], v[40:43]
	v_add_u32_e32 v140, s31, v237
	v_mfma_f32_16x16x32_bf16 v[28:31], v[180:183], v[156:159], v[28:31]
	s_add_u32 s74, s74, s20
	v_mfma_f32_16x16x32_bf16 v[24:27], v[188:191], v[156:159], v[24:27]
	s_addc_u32 s75, s75, 0
	v_mfma_f32_16x16x32_bf16 v[12:15], v[180:183], v[164:167], v[12:15]
	s_mov_b32 m0, s34
	v_mfma_f32_16x16x32_bf16 v[8:11], v[188:191], v[164:167], v[8:11]
	v_lshl_add_u64 v[176:177], s[74:75], 0, v[194:195]
	v_mfma_f32_16x16x32_bf16 v[4:7], v[180:183], v[172:175], v[4:7]
	v_lshl_add_u64 v[178:179], s[74:75], 0, v[198:199]
	v_mfma_f32_16x16x32_bf16 v[0:3], v[188:191], v[172:175], v[0:3]
	s_barrier
	ds_read_b128 v[128:131], v140
	ds_read_b128 v[132:135], v140 offset:1024
	ds_read_b128 v[136:139], v140 offset:2048
	ds_read_b128 v[140:143], v140 offset:3072
	ds_read_b128 v[144:147], v240 offset:32768
	ds_read_b128 v[148:151], v240 offset:33792
	ds_read_b128 v[152:155], v240 offset:34816
	ds_read_b128 v[156:159], v240 offset:35840
	ds_read_b128 v[160:163], v240 offset:36864
	ds_read_b128 v[164:167], v240 offset:37888
	ds_read_b128 v[168:171], v240 offset:38912
	ds_read_b128 v[172:175], v240 offset:39936
	global_load_lds_dwordx4 v[176:177], off
	s_mov_b32 m0, s35
	s_nop 0
	global_load_lds_dwordx4 v[178:179], off
	s_waitcnt lgkmcnt(8)
	s_barrier
	s_waitcnt lgkmcnt(0)
	v_mfma_f32_16x16x32_bf16 v[124:127], v[128:131], v[144:147], v[124:127]
	v_mfma_f32_16x16x32_bf16 v[120:123], v[136:139], v[144:147], v[120:123]
	v_mfma_f32_16x16x32_bf16 v[116:119], v[128:131], v[152:155], v[116:119]
	v_mfma_f32_16x16x32_bf16 v[112:115], v[136:139], v[152:155], v[112:115]
	v_mfma_f32_16x16x32_bf16 v[100:103], v[128:131], v[160:163], v[100:103]
	v_mfma_f32_16x16x32_bf16 v[96:99], v[136:139], v[160:163], v[96:99]
	v_mfma_f32_16x16x32_bf16 v[84:87], v[128:131], v[168:171], v[84:87]
	v_mfma_f32_16x16x32_bf16 v[80:83], v[136:139], v[168:171], v[80:83]
	v_mfma_f32_16x16x32_bf16 v[124:127], v[132:135], v[148:151], v[124:127]
	s_add_i32 s74, 0, 0x1c000
	v_mfma_f32_16x16x32_bf16 v[120:123], v[140:143], v[148:151], v[120:123]
	s_add_i32 s31, s31, s87
	v_mfma_f32_16x16x32_bf16 v[116:119], v[132:135], v[156:159], v[116:119]
	v_add_u32_e32 v188, s74, v237
	v_mfma_f32_16x16x32_bf16 v[112:115], v[140:143], v[156:159], v[112:115]
	v_lshl_add_u64 v[210:211], v[210:211], 0, s[60:61]
	v_mfma_f32_16x16x32_bf16 v[100:103], v[132:135], v[164:167], v[100:103]
	s_mov_b32 m0, s31
	v_mfma_f32_16x16x32_bf16 v[96:99], v[140:143], v[164:167], v[96:99]
	v_mfma_f32_16x16x32_bf16 v[84:87], v[132:135], v[172:175], v[84:87]
	v_mfma_f32_16x16x32_bf16 v[80:83], v[140:143], v[172:175], v[80:83]
	s_barrier
	ds_read_b128 v[176:179], v188
	ds_read_b128 v[180:183], v188 offset:1024
	ds_read_b128 v[184:187], v188 offset:2048
	ds_read_b128 v[188:191], v188 offset:3072
	global_load_lds_dwordx4 v[210:211], off
	v_lshl_add_u64 v[210:211], v[212:213], 0, s[60:61]
	s_add_i32 m0, s31, 0x2000
	s_nop 0
	global_load_lds_dwordx4 v[210:211], off
	s_barrier
	s_waitcnt lgkmcnt(0)
	v_mfma_f32_16x16x32_bf16 v[108:111], v[176:179], v[144:147], v[108:111]
	v_mfma_f32_16x16x32_bf16 v[104:107], v[184:187], v[144:147], v[104:107]
	v_mfma_f32_16x16x32_bf16 v[92:95], v[176:179], v[152:155], v[92:95]
	v_mfma_f32_16x16x32_bf16 v[88:91], v[184:187], v[152:155], v[88:91]
	v_mfma_f32_16x16x32_bf16 v[76:79], v[176:179], v[160:163], v[76:79]
	v_mfma_f32_16x16x32_bf16 v[72:75], v[184:187], v[160:163], v[72:75]
	v_mfma_f32_16x16x32_bf16 v[68:71], v[176:179], v[168:171], v[68:71]
	v_mfma_f32_16x16x32_bf16 v[64:67], v[184:187], v[168:171], v[64:67]
	v_mfma_f32_16x16x32_bf16 v[108:111], v[180:183], v[148:151], v[108:111]
	s_mov_b32 m0, s97
	v_mfma_f32_16x16x32_bf16 v[104:107], v[188:191], v[148:151], v[104:107]
	v_lshl_add_u64 v[210:211], v[214:215], 0, s[60:61]
	v_mfma_f32_16x16x32_bf16 v[92:95], v[180:183], v[156:159], v[92:95]
	v_mfma_f32_16x16x32_bf16 v[88:91], v[188:191], v[156:159], v[88:91]
	v_mfma_f32_16x16x32_bf16 v[76:79], v[180:183], v[164:167], v[76:79]
	v_mfma_f32_16x16x32_bf16 v[72:75], v[188:191], v[164:167], v[72:75]
	v_mfma_f32_16x16x32_bf16 v[68:71], v[180:183], v[172:175], v[68:71]
	v_mfma_f32_16x16x32_bf16 v[64:67], v[188:191], v[172:175], v[64:67]
	s_barrier
	ds_read_b128 v[144:147], v240 offset:49152
	ds_read_b128 v[148:151], v240 offset:50176
	ds_read_b128 v[152:155], v240 offset:51200
	ds_read_b128 v[156:159], v240 offset:52224
	ds_read_b128 v[160:163], v240 offset:53248
	ds_read_b128 v[164:167], v240 offset:54272
	ds_read_b128 v[168:171], v240 offset:55296
	ds_read_b128 v[172:175], v240 offset:56320
	global_load_lds_dwordx4 v[210:211], off
	v_lshl_add_u64 v[210:211], v[216:217], 0, s[60:61]
	s_mov_b32 m0, s36
	s_nop 0
	global_load_lds_dwordx4 v[210:211], off
	s_barrier
	s_waitcnt lgkmcnt(0)
	v_mfma_f32_16x16x32_bf16 v[60:63], v[128:131], v[144:147], v[60:63]
	v_mfma_f32_16x16x32_bf16 v[56:59], v[136:139], v[144:147], v[56:59]
	v_mfma_f32_16x16x32_bf16 v[52:55], v[128:131], v[152:155], v[52:55]
	v_mfma_f32_16x16x32_bf16 v[48:51], v[136:139], v[152:155], v[48:51]
	v_mfma_f32_16x16x32_bf16 v[36:39], v[128:131], v[160:163], v[36:39]
	v_mfma_f32_16x16x32_bf16 v[32:35], v[136:139], v[160:163], v[32:35]
	v_mfma_f32_16x16x32_bf16 v[20:23], v[128:131], v[168:171], v[20:23]
	v_mfma_f32_16x16x32_bf16 v[16:19], v[136:139], v[168:171], v[16:19]
	v_mfma_f32_16x16x32_bf16 v[60:63], v[132:135], v[148:151], v[60:63]
	s_add_i32 s31, s74, s87
	v_mfma_f32_16x16x32_bf16 v[56:59], v[140:143], v[148:151], v[56:59]
	v_lshl_add_u64 v[128:129], v[218:219], 0, s[60:61]
	v_mfma_f32_16x16x32_bf16 v[52:55], v[132:135], v[156:159], v[52:55]
	s_mov_b32 m0, s31
	v_mfma_f32_16x16x32_bf16 v[48:51], v[140:143], v[156:159], v[48:51]
	v_mfma_f32_16x16x32_bf16 v[36:39], v[132:135], v[164:167], v[36:39]
	v_mfma_f32_16x16x32_bf16 v[32:35], v[140:143], v[164:167], v[32:35]
	v_mfma_f32_16x16x32_bf16 v[20:23], v[132:135], v[172:175], v[20:23]
	v_mfma_f32_16x16x32_bf16 v[16:19], v[140:143], v[172:175], v[16:19]
	s_barrier
	s_nop 0
	global_load_lds_dwordx4 v[128:129], off
	v_lshl_add_u64 v[128:129], v[220:221], 0, s[60:61]
	s_add_i32 m0, s31, 0x2000
	s_nop 0
	global_load_lds_dwordx4 v[128:129], off
	s_waitcnt vmcnt(6)
	s_barrier
	v_mfma_f32_16x16x32_bf16 v[44:47], v[176:179], v[144:147], v[44:47]
	s_add_u32 s72, s72, 0x100
	v_mfma_f32_16x16x32_bf16 v[40:43], v[184:187], v[144:147], v[40:43]
	s_addc_u32 s73, s73, 0
	v_mfma_f32_16x16x32_bf16 v[28:31], v[176:179], v[152:155], v[28:31]
	s_add_u32 s78, s78, 0x100
	v_mfma_f32_16x16x32_bf16 v[24:27], v[184:187], v[152:155], v[24:27]
	s_addc_u32 s79, s79, 0
	v_mfma_f32_16x16x32_bf16 v[12:15], v[176:179], v[160:163], v[12:15]
	s_add_i32 vcc_hi, 0, 0x10000
	v_mfma_f32_16x16x32_bf16 v[8:11], v[184:187], v[160:163], v[8:11]
	v_add_u32_e32 v140, vcc_hi, v237
	v_mfma_f32_16x16x32_bf16 v[4:7], v[176:179], v[168:171], v[4:7]
	s_add_i32 m0, s93, 0xc000
	v_mfma_f32_16x16x32_bf16 v[0:3], v[184:187], v[168:171], v[0:3]
	s_cmp_ge_u32 vcc_lo, s30
	v_mfma_f32_16x16x32_bf16 v[44:47], v[180:183], v[148:151], v[44:47]
	s_mov_b32 s74, vcc_lo
	v_mfma_f32_16x16x32_bf16 v[40:43], v[188:191], v[148:151], v[40:43]
	v_mfma_f32_16x16x32_bf16 v[28:31], v[180:183], v[156:159], v[28:31]
	v_lshl_add_u64 v[176:177], s[72:73], 0, v[206:207]
	v_mfma_f32_16x16x32_bf16 v[24:27], v[188:191], v[156:159], v[24:27]
	v_mfma_f32_16x16x32_bf16 v[12:15], v[180:183], v[164:167], v[12:15]
	v_lshl_add_u64 v[178:179], s[72:73], 0, v[208:209]
	v_mfma_f32_16x16x32_bf16 v[8:11], v[188:191], v[164:167], v[8:11]
	v_mfma_f32_16x16x32_bf16 v[4:7], v[180:183], v[172:175], v[4:7]
	v_mfma_f32_16x16x32_bf16 v[0:3], v[188:191], v[172:175], v[0:3]
	s_barrier
	s_cbranch_scc0 .LBB0_522
	s_cmp_lt_i32 s91, 0
	s_mov_b64 s[72:73], -1
	s_cbranch_scc0 .LBB0_716
	s_lshl_b32 s78, s46, 8
	s_cmp_lt_i32 s81, 2
	s_cbranch_scc1 .LBB0_582
	s_cmp_lt_i32 s81, 3
	s_cbranch_scc1 .LBB0_579
	s_cmp_lg_u32 s81, 3
	s_cbranch_scc0 .LBB0_544
	v_lshl_or_b32 v128, s19, 7, v238
	v_ashrrev_i32_e32 v129, 31, v128
	v_lshl_add_u64 v[144:145], v[128:129], 1, s[24:25]
	v_and_b32_e32 v129, 64, v231
	v_xor_b32_e32 v128, 16, v231
	v_add_u32_e32 v129, 64, v129
	v_cmp_lt_i32_e32 vcc, v128, v129
	v_add_u32_e32 v146, s78, v202
	v_ashrrev_i32_e32 v147, 31, v146
	v_cndmask_b32_e32 v128, v231, v128, vcc
	v_lshlrev_b32_e32 v167, 2, v128
	v_xor_b32_e32 v128, 32, v231
	v_cmp_lt_i32_e32 vcc, v128, v129
	v_or_b32_e32 v156, 16, v146
	v_ashrrev_i32_e32 v157, 31, v156
	v_cndmask_b32_e32 v128, v231, v128, vcc
	v_lshlrev_b32_e32 v166, 2, v128
	v_lshlrev_b64 v[128:129], 12, v[146:147]
	v_lshl_add_u64 v[160:161], v[144:145], 0, v[128:129]
	global_load_dwordx4 v[140:143], v[160:161], off
	v_or_b32_e32 v152, 32, v146
	v_lshlrev_b64 v[128:129], 12, v[156:157]
	v_ashrrev_i32_e32 v153, 31, v152
	v_or_b32_e32 v148, 48, v146
	v_lshl_add_u64 v[158:159], v[144:145], 0, v[128:129]
	v_lshlrev_b64 v[128:129], 12, v[152:153]
	v_ashrrev_i32_e32 v149, 31, v148
	v_lshl_add_u64 v[154:155], v[144:145], 0, v[128:129]
	v_lshlrev_b64 v[128:129], 12, v[148:149]
	v_lshl_add_u64 v[150:151], v[144:145], 0, v[128:129]
	global_load_dwordx4 v[136:139], v[158:159], off
	global_load_dwordx4 v[132:135], v[154:155], off
	global_load_dwordx4 v[128:131], v[150:151], off
	v_mul_f32_e32 v163, 0xbfb8aa3b, v104
	v_exp_f32_e32 v163, v163
	v_mul_f32_e32 v162, 0xbfb8aa3b, v108
	v_exp_f32_e32 v162, v162
	v_add_f32_e32 v163, 1.0, v163
	v_rcp_f32_e32 v164, v163
	v_mul_f32_e32 v163, 0xbfb8aa3b, v109
	v_exp_f32_e32 v163, v163
	v_add_f32_e32 v162, 1.0, v162
	v_rcp_f32_e32 v162, v162
	v_add_f32_e32 v163, 1.0, v163
	v_rcp_f32_e32 v163, v163
	s_waitcnt vmcnt(0)
	v_lshlrev_b32_e32 v168, 16, v140
	v_and_b32_e32 v169, 0xffff0000, v140
	v_mul_f32_e32 v140, 0xbfb8aa3b, v105
	v_exp_f32_e32 v140, v140
	v_pk_fma_f32 v[162:163], v[162:163], v[124:125], v[168:169]
	v_lshlrev_b32_e32 v168, 16, v142
	v_and_b32_e32 v169, 0xffff0000, v142
	v_add_f32_e32 v140, 1.0, v140
	v_rcp_f32_e32 v165, v140
	v_mul_f32_e32 v140, 0xbfb8aa3b, v110
	v_exp_f32_e32 v140, v140
	v_mul_f32_e32 v142, 0xbfb8aa3b, v111
	v_pk_fma_f32 v[164:165], v[164:165], v[120:121], v[168:169]
	v_lshlrev_b32_e32 v170, 16, v141
	v_add_f32_e32 v140, 1.0, v140
	v_rcp_f32_e32 v168, v140
	v_mul_f32_e32 v140, 0xbfb8aa3b, v106
	v_and_b32_e32 v171, 0xffff0000, v141
	v_mul_f32_e32 v141, 0xbfb8aa3b, v107
	v_exp_f32_e32 v140, v140
	v_exp_f32_e32 v142, v142
	v_exp_f32_e32 v141, v141
	v_add_f32_e32 v140, 1.0, v140
	v_add_f32_e32 v142, 1.0, v142
	v_add_f32_e32 v141, 1.0, v141
	v_rcp_f32_e32 v140, v140
	v_rcp_f32_e32 v169, v142
	v_rcp_f32_e32 v141, v141
	v_lshlrev_b32_e32 v142, 16, v143
	v_and_b32_e32 v143, 0xffff0000, v143
	v_pk_fma_f32 v[168:169], v[168:169], v[126:127], v[170:171]
	v_pk_fma_f32 v[170:171], v[140:141], v[122:123], v[142:143]
	v_cvt_pk_bf16_f32 v140, v162, v163
	v_cvt_pk_bf16_f32 v141, v168, v169
	v_cvt_pk_bf16_f32 v142, v164, v165
	v_cvt_pk_bf16_f32 v143, v170, v171
	global_store_dwordx4 v[160:161], v[140:143], off
	v_pk_mul_f32 v[160:161], v[164:165], v[164:165]
	s_nop 0
	v_pk_mul_f32 v[140:141], v[162:163], v[162:163]
	v_pk_mul_f32 v[142:143], v[168:169], v[168:169]
	v_add_f32_e32 v140, v140, v141
	v_add_f32_e32 v142, v142, v143
	v_pk_mul_f32 v[162:163], v[170:171], v[170:171]
	v_add_f32_e32 v140, v140, v142
	v_add_f32_e32 v141, v160, v161
	v_add_f32_e32 v162, v162, v163
	v_add_f32_e32 v140, v141, v140
	v_add_f32_e32 v140, v162, v140
	v_mov_b32_e32 v141, v140
	s_nop 1
	v_permlane16_swap_b32_e32 v141, v140
	s_waitcnt lgkmcnt(0)
	v_add_f32_e32 v140, v140, v141
	v_mov_b32_e32 v141, v140
	s_nop 1
	v_permlane32_swap_b32_e32 v141, v140
	s_and_saveexec_b64 s[72:73], s[6:7]
	s_cbranch_execz .LBB0_529
	s_waitcnt lgkmcnt(0)
	v_add_f32_e32 v142, v140, v141
	s_lshl_b32 s74, s19, 2
	v_lshlrev_b64 v[140:141], 8, v[146:147]
	s_ashr_i32 s75, s74, 31
	v_lshl_add_u64 v[140:141], s[26:27], 0, v[140:141]
	v_lshl_add_u64 v[140:141], s[74:75], 2, v[140:141]
	s_lshl_b32 s50, s37, 2
	v_lshl_add_u64 v[140:141], v[140:141], 0, s[50:51]
	global_store_dword v[140:141], v142, off
